# grid barrier cross-XCD stage: non-last XCD leaders spin on the TOP arrival counter reaching its target instead of on TOPGEN (one memory round trip fewer on the release path)
# speedup vs baseline: 1.0154x; 1.0063x over previous
; __device__ __forceinline__ unsigned xb_ld(unsigned* p)              { return __hip_atomic_load(p, __ATOMIC_RELAXED, __HIP_MEMORY_SCOPE_AGENT); }
; __device__ __forceinline__ unsigned xb_add(unsigned* p, unsigned v) { return __hip_atomic_fetch_add(p, v, __ATOMIC_RELAXED, __HIP_MEMORY_SCOPE_AGENT); }
; #define XB_SPIN(cond, bar) do { unsigned _sp = 0; while (cond) { __builtin_amdgcn_s_sleep(1); \
;     if ((++_sp & 255u) == 0u) { if (xb_ld(&(bar)[XB_TMO])) break; if (_sp > XB_SPIN_CAP) { atomicAdd(&(bar)[XB_TMO], 1u); break; } } } } while (0)
; __device__ __forceinline__ void xcd_barrier(const XcdBarrier& b) {
;     ...
;         const unsigned old = xb_add(&bar[XB_XSUB(b.x)], 1u);
;         const unsigned gen = old / nloc;
;         if (old + 1u == (gen + 1u) * nloc) {
;             __builtin_amdgcn_fence(__ATOMIC_RELEASE, "agent");
;             asm volatile("s_waitcnt vmcnt(0)" ::: "memory");
;             const unsigned og = xb_add(&bar[XB_TOP], 1u);
;             const unsigned tg = og / nx;
;             if (og + 1u == (tg + 1u) * nx) xb_add(&bar[XB_TOPGEN], 1u);
;             else XB_SPIN(xb_ld(&bar[XB_TOPGEN]) == tg, bar);
.LBB0_395:
	s_or_b64 exec, exec, s[20:21]
	s_waitcnt vmcnt(0)
	v_readfirstlane_b32 s8, v3
	v_sub_u32_e32 v4, 0, v2
	v_readlane_b32 s14, v253, 24
	v_add_u32_e32 v3, s8, v1
	v_cvt_f32_u32_e32 v1, v2
	v_readlane_b32 s15, v253, 25
	s_mov_b64 s[20:21], -1
	v_rcp_iflag_f32_e32 v1, v1
	s_nop 0
	v_mul_f32_e32 v1, 0x4f7ffffe, v1
	v_cvt_u32_f32_e32 v1, v1
	v_mul_lo_u32 v4, v4, v1
	v_mul_hi_u32 v4, v1, v4
	v_add_u32_e32 v1, v1, v4
	v_mul_hi_u32 v1, v3, v1
	v_mul_lo_u32 v4, v1, v2
	v_sub_u32_e32 v4, v3, v4
	v_cmp_ge_u32_e32 vcc, v4, v2
	v_add_u32_e32 v5, 1, v1
	v_add_u32_e32 v3, 1, v3
	v_cndmask_b32_e32 v1, v1, v5, vcc
	v_sub_u32_e32 v5, v4, v2
	v_cndmask_b32_e32 v4, v4, v5, vcc
	v_cmp_ge_u32_e32 vcc, v4, v2
	v_add_u32_e32 v4, 1, v1
	s_nop 0
	v_cndmask_b32_e32 v1, v1, v4, vcc
	v_mul_lo_u32 v4, v2, v1
	v_add_u32_e32 v2, v4, v2
	v_cmp_ne_u32_e32 vcc, v3, v2
	v_mov_b32_e32 v6, v2
	v_mov_b64_e32 v[2:3], s[14:15]
	s_and_saveexec_b64 s[18:19], vcc
	s_cbranch_execz .LBB0_407
	v_readlane_b32 s14, v253, 22
	v_readlane_b32 s15, v253, 23
	s_mov_b64 s[22:23], 0
	s_nop 3
	global_load_dword v2, v99, s[14:15] sc1
	s_waitcnt vmcnt(0)
	v_cmp_lt_u32_e32 vcc, v2, v6
	s_and_saveexec_b64 s[20:21], vcc
	s_cbranch_execz .LBB0_406
	s_mov_b32 s8, 1
	s_branch .LBB0_399

; __device__ __forceinline__ unsigned xb_ld(unsigned* p)              { return __hip_atomic_load(p, __ATOMIC_RELAXED, __HIP_MEMORY_SCOPE_AGENT); }
; #define XB_SPIN(cond, bar) do { unsigned _sp = 0; while (cond) { __builtin_amdgcn_s_sleep(1); \
;     if ((++_sp & 255u) == 0u) { if (xb_ld(&(bar)[XB_TMO])) break; if (_sp > XB_SPIN_CAP) { atomicAdd(&(bar)[XB_TMO], 1u); break; } } } } while (0)
; __device__ __forceinline__ void xcd_barrier(const XcdBarrier& b) {
;     ...
;             else XB_SPIN(xb_ld(&bar[XB_TOPGEN]) == tg, bar);
.LBB0_401:
	v_readlane_b32 s14, v253, 22
	v_readlane_b32 s15, v253, 23
	s_add_i32 s8, s8, 1
	s_mov_b64 s[28:29], -1
	s_nop 2
	global_load_dword v2, v99, s[14:15] sc1
	s_waitcnt vmcnt(0)
	v_cmp_ge_u32_e32 vcc, v2, v6
	s_orn2_b64 s[26:27], vcc, exec
	s_branch .LBB0_398

; __device__ __forceinline__ unsigned xb_ld(unsigned* p)              { return __hip_atomic_load(p, __ATOMIC_RELAXED, __HIP_MEMORY_SCOPE_AGENT); }
; __device__ __forceinline__ unsigned xb_add(unsigned* p, unsigned v) { return __hip_atomic_fetch_add(p, v, __ATOMIC_RELAXED, __HIP_MEMORY_SCOPE_AGENT); }
; #define XB_SPIN(cond, bar) do { unsigned _sp = 0; while (cond) { __builtin_amdgcn_s_sleep(1); \
;     if ((++_sp & 255u) == 0u) { if (xb_ld(&(bar)[XB_TMO])) break; if (_sp > XB_SPIN_CAP) { atomicAdd(&(bar)[XB_TMO], 1u); break; } } } } while (0)
; __device__ __forceinline__ void xcd_barrier(const XcdBarrier& b) {
;     ...
;         const unsigned old = xb_add(&bar[XB_XSUB(b.x)], 1u);
;         const unsigned gen = old / nloc;
;         if (old + 1u == (gen + 1u) * nloc) {
;             __builtin_amdgcn_fence(__ATOMIC_RELEASE, "agent");
;             asm volatile("s_waitcnt vmcnt(0)" ::: "memory");
;             const unsigned og = xb_add(&bar[XB_TOP], 1u);
;             const unsigned tg = og / nx;
;             if (og + 1u == (tg + 1u) * nx) xb_add(&bar[XB_TOPGEN], 1u);
;             else XB_SPIN(xb_ld(&bar[XB_TOPGEN]) == tg, bar);
.LBB0_630:
	s_or_b64 exec, exec, s[22:23]
	s_waitcnt vmcnt(0)
	v_readfirstlane_b32 s8, v3
	v_sub_u32_e32 v4, 0, v2
	v_readlane_b32 s14, v253, 24
	v_add_u32_e32 v3, s8, v1
	v_cvt_f32_u32_e32 v1, v2
	v_readlane_b32 s15, v253, 25
	s_mov_b64 s[22:23], -1
	v_rcp_iflag_f32_e32 v1, v1
	s_nop 0
	v_mul_f32_e32 v1, 0x4f7ffffe, v1
	v_cvt_u32_f32_e32 v1, v1
	v_mul_lo_u32 v4, v4, v1
	v_mul_hi_u32 v4, v1, v4
	v_add_u32_e32 v1, v1, v4
	v_mul_hi_u32 v1, v3, v1
	v_mul_lo_u32 v4, v1, v2
	v_sub_u32_e32 v4, v3, v4
	v_cmp_ge_u32_e32 vcc, v4, v2
	v_add_u32_e32 v5, 1, v1
	v_add_u32_e32 v3, 1, v3
	v_cndmask_b32_e32 v1, v1, v5, vcc
	v_sub_u32_e32 v5, v4, v2
	v_cndmask_b32_e32 v4, v4, v5, vcc
	v_cmp_ge_u32_e32 vcc, v4, v2
	v_add_u32_e32 v4, 1, v1
	s_nop 0
	v_cndmask_b32_e32 v1, v1, v4, vcc
	v_mul_lo_u32 v4, v2, v1
	v_add_u32_e32 v2, v4, v2
	v_cmp_ne_u32_e32 vcc, v3, v2
	v_mov_b32_e32 v6, v2
	v_mov_b64_e32 v[2:3], s[14:15]
	s_and_saveexec_b64 s[20:21], vcc
	s_cbranch_execz .LBB0_642
	v_readlane_b32 s14, v253, 22
	v_readlane_b32 s15, v253, 23
	s_mov_b64 s[24:25], 0
	s_nop 3
	global_load_dword v2, v99, s[14:15] sc1
	s_waitcnt vmcnt(0)
	v_cmp_lt_u32_e32 vcc, v2, v6
	s_and_saveexec_b64 s[22:23], vcc
	s_cbranch_execz .LBB0_641
	s_mov_b32 s8, 1
	s_branch .LBB0_634

; __device__ __forceinline__ unsigned xb_ld(unsigned* p)              { return __hip_atomic_load(p, __ATOMIC_RELAXED, __HIP_MEMORY_SCOPE_AGENT); }
; #define XB_SPIN(cond, bar) do { unsigned _sp = 0; while (cond) { __builtin_amdgcn_s_sleep(1); \
;     if ((++_sp & 255u) == 0u) { if (xb_ld(&(bar)[XB_TMO])) break; if (_sp > XB_SPIN_CAP) { atomicAdd(&(bar)[XB_TMO], 1u); break; } } } } while (0)
; __device__ __forceinline__ void xcd_barrier(const XcdBarrier& b) {
;     ...
;             else XB_SPIN(xb_ld(&bar[XB_TOPGEN]) == tg, bar);
.LBB0_636:
	v_readlane_b32 s14, v253, 22
	v_readlane_b32 s15, v253, 23
	s_add_i32 s8, s8, 1
	s_mov_b64 s[30:31], -1
	s_nop 2
	global_load_dword v2, v99, s[14:15] sc1
	s_waitcnt vmcnt(0)
	v_cmp_ge_u32_e32 vcc, v2, v6
	s_orn2_b64 s[28:29], vcc, exec
	s_branch .LBB0_633

; __device__ __forceinline__ unsigned xb_ld(unsigned* p)              { return __hip_atomic_load(p, __ATOMIC_RELAXED, __HIP_MEMORY_SCOPE_AGENT); }
; __device__ __forceinline__ unsigned xb_add(unsigned* p, unsigned v) { return __hip_atomic_fetch_add(p, v, __ATOMIC_RELAXED, __HIP_MEMORY_SCOPE_AGENT); }
; #define XB_SPIN(cond, bar) do { unsigned _sp = 0; while (cond) { __builtin_amdgcn_s_sleep(1); \
;     if ((++_sp & 255u) == 0u) { if (xb_ld(&(bar)[XB_TMO])) break; if (_sp > XB_SPIN_CAP) { atomicAdd(&(bar)[XB_TMO], 1u); break; } } } } while (0)
; __device__ __forceinline__ void xcd_barrier(const XcdBarrier& b) {
;     ...
;         const unsigned old = xb_add(&bar[XB_XSUB(b.x)], 1u);
;         const unsigned gen = old / nloc;
;         if (old + 1u == (gen + 1u) * nloc) {
;             __builtin_amdgcn_fence(__ATOMIC_RELEASE, "agent");
;             asm volatile("s_waitcnt vmcnt(0)" ::: "memory");
;             const unsigned og = xb_add(&bar[XB_TOP], 1u);
;             const unsigned tg = og / nx;
;             if (og + 1u == (tg + 1u) * nx) xb_add(&bar[XB_TOPGEN], 1u);
;             else XB_SPIN(xb_ld(&bar[XB_TOPGEN]) == tg, bar);
.LBB0_1536:
	s_or_b64 exec, exec, s[18:19]
	s_waitcnt vmcnt(0)
	v_readfirstlane_b32 s4, v3
	v_sub_u32_e32 v4, 0, v2
	v_readlane_b32 s14, v253, 24
	v_add_u32_e32 v3, s4, v1
	v_cvt_f32_u32_e32 v1, v2
	v_readlane_b32 s15, v253, 25
	s_mov_b64 s[18:19], -1
	v_rcp_iflag_f32_e32 v1, v1
	s_nop 0
	v_mul_f32_e32 v1, 0x4f7ffffe, v1
	v_cvt_u32_f32_e32 v1, v1
	v_mul_lo_u32 v4, v4, v1
	v_mul_hi_u32 v4, v1, v4
	v_add_u32_e32 v1, v1, v4
	v_mul_hi_u32 v1, v3, v1
	v_mul_lo_u32 v4, v1, v2
	v_sub_u32_e32 v4, v3, v4
	v_cmp_ge_u32_e32 vcc, v4, v2
	v_add_u32_e32 v5, 1, v1
	v_add_u32_e32 v3, 1, v3
	v_cndmask_b32_e32 v1, v1, v5, vcc
	v_sub_u32_e32 v5, v4, v2
	v_cndmask_b32_e32 v4, v4, v5, vcc
	v_cmp_ge_u32_e32 vcc, v4, v2
	v_add_u32_e32 v4, 1, v1
	s_nop 0
	v_cndmask_b32_e32 v1, v1, v4, vcc
	v_mul_lo_u32 v4, v2, v1
	v_add_u32_e32 v2, v4, v2
	v_cmp_ne_u32_e32 vcc, v3, v2
	v_mov_b32_e32 v6, v2
	v_mov_b64_e32 v[2:3], s[14:15]
	s_and_saveexec_b64 s[14:15], vcc
	s_cbranch_execz .LBB0_1548
	v_readlane_b32 s16, v253, 22
	v_readlane_b32 s17, v253, 23
	s_mov_b64 s[20:21], 0
	s_nop 3
	global_load_dword v2, v99, s[16:17] sc1
	s_waitcnt vmcnt(0)
	v_cmp_lt_u32_e32 vcc, v2, v6
	s_and_saveexec_b64 s[18:19], vcc
	s_cbranch_execz .LBB0_1547
	s_mov_b32 s4, 1
	s_branch .LBB0_1540

; __device__ __forceinline__ unsigned xb_ld(unsigned* p)              { return __hip_atomic_load(p, __ATOMIC_RELAXED, __HIP_MEMORY_SCOPE_AGENT); }
; #define XB_SPIN(cond, bar) do { unsigned _sp = 0; while (cond) { __builtin_amdgcn_s_sleep(1); \
;     if ((++_sp & 255u) == 0u) { if (xb_ld(&(bar)[XB_TMO])) break; if (_sp > XB_SPIN_CAP) { atomicAdd(&(bar)[XB_TMO], 1u); break; } } } } while (0)
; __device__ __forceinline__ void xcd_barrier(const XcdBarrier& b) {
;     ...
;             else XB_SPIN(xb_ld(&bar[XB_TOPGEN]) == tg, bar);
.LBB0_1542:
	v_readlane_b32 s16, v253, 22
	v_readlane_b32 s17, v253, 23
	s_add_i32 s4, s4, 1
	s_mov_b64 s[26:27], -1
	s_nop 2
	global_load_dword v2, v99, s[16:17] sc1
	s_waitcnt vmcnt(0)
	v_cmp_ge_u32_e32 vcc, v2, v6
	s_orn2_b64 s[24:25], vcc, exec
	s_branch .LBB0_1539
